# v43 plus a ~128-cycle start-of-tile delay for waves 0-3 in the C loop (stagger test)
# baseline (speedup 1.0000x reference)
; #define MFMA32(a, b, c) __builtin_amdgcn_mfma_f32_32x32x16_bf16((a), (b), (c), 0, 0, 0)
; template <int MODE>
; DI void attn_unit(unsigned char* lds, const AttnParams& ap, int b, int h, int qb, int tid) {
;     ...
;   const int qpos = qb * 256 + wave * 32 + r32, cw = qb * 4 + (wave >> 1);
;   bf16x8 qf[4];
;   { const bf16_t* qp = ap.P + (tokb + qpos) * PLD + qcol0 + h * 64 + 8 * hi;
; #pragma unroll
;     for (int ks = 0; ks < 4; ++ks) qf[ks] = *(const bf16x8*)(qp + 16 * ks); }
;   bf16_t* Ks0 = (bf16_t*)lds; bf16_t* Vs0 = Ks0 + NCH * 64 * 72; volatile int* flags = (volatile int*)(lds + 2 * NCH * 64 * 72 * 2);
;   const int jhi = 4 * qb + 3, jlo = (MODE == 0) ? ((4 * qb - 8 > 0) ? 4 * qb - 8 : 0) : 0, ntiles = jhi - jlo + 1;
;   const int lrow = tid >> 3, lch = tid & 7;
;   const bf16_t* kg = ap.P + (tokb + lrow) * PLD + kcol0 + h * 64 + 8 * lch;
;   const bf16_t* vg = Vt + (size_t)bh * 256 * 4096 + lrow * 64 + 8 * lch;
;   const int j0 = (MODE == 2) ? jhi : jlo;
;   u32x4 kreg[NCH], vreg[NCH];
; #pragma unroll
;   for (int c = 0; c < NCH; ++c) { const int jc = (MODE == 2) ? j0 - c : j0 + c; kreg[c] = *(const u32x4*)(kg + (size_t)jc * 64 * PLD); vreg[c] = *(const u32x4*)(vg + (size_t)jc * 4096); }
;   f32x16 O0[2], O1[2]; float l0 = 0.f, l1 = 0.f, cum = 0.f;
; #pragma unroll
;   for (int eb = 0; eb < 2; ++eb) { O0[eb] = splat16(0.f); O1[eb] = splat16(0.f); }
;     ...
;         { f32x16 s0 = splat16(ap.negM);
;           s0 = MFMA32(*(const bf16x8*)(kb), qf[0], s0); s0 = MFMA32(*(const bf16x8*)(kb + 16), qf[1], s0);
.LBB0_845:
	v_readlane_b32 s0, v255, 51
	v_readlane_b32 s1, v255, 52
	s_andn2_saveexec_b64 s[6:7], s[0:1]
	s_cbranch_execz .LBB0_853
	v_mov_b32_e32 v1, v156
	v_readlane_b32 s0, v255, 25
	v_ashrrev_i32_e32 v2, 1, v1
	v_and_b32_e32 v2, 0xffffffe0, v2
	v_and_b32_e32 v7, 31, v1
	v_lshl_add_u32 v2, v0, 8, v2
	v_or_b32_e32 v2, v2, v7
	v_lshlrev_b32_e32 v32, 14, v4
	v_ashrrev_i32_e32 v3, 31, v2
	v_readlane_b32 s1, v255, 26
	v_lshl_add_u64 v[134:135], v[2:3], 0, v[32:33]
	v_bfe_u32 v47, v1, 5, 1
	v_mov_b64_e32 v[2:3], s[0:1]
	v_mad_u64_u32 v[8:9], s[0:1], v134, s82, v[2:3]
	v_mad_i32_i24 v9, v135, s82, v9
	v_lshlrev_b32_e32 v10, 7, v5
	v_mov_b32_e32 v11, v33
	v_lshl_add_u64 v[8:9], v[8:9], 0, v[10:11]
	v_lshlrev_b32_e32 v132, 4, v47
	v_mov_b32_e32 v133, v33
	v_lshl_add_u64 v[8:9], v[8:9], 0, v[132:133]
	v_ashrrev_i32_e32 v14, 3, v1
	global_load_dwordx4 v[112:115], v[8:9], off offset:3584
	global_load_dwordx4 v[42:45], v[8:9], off offset:3616
	global_load_dwordx4 v[38:41], v[8:9], off offset:3648
	global_load_dwordx4 v[34:37], v[8:9], off offset:3680
	v_add_u32_e32 v8, v14, v32
	v_mad_i64_i32 v[2:3], s[0:1], v8, s82, v[2:3]
	v_lshlrev_b32_e32 v8, 4, v1
	v_and_b32_e32 v32, 0x70, v8
	v_lshlrev_b32_e32 v8, 21, v5
	v_readlane_b32 s0, v255, 41
	v_lshl_add_u64 v[2:3], v[2:3], 0, v[10:11]
	v_lshl_or_b32 v8, v4, 23, v8
	v_mov_b32_e32 v9, v33
	v_readlane_b32 s1, v255, 42
	v_lshlrev_b32_e32 v12, 6, v14
	v_lshl_add_u64 v[2:3], v[2:3], 0, v[32:33]
	v_lshl_add_u64 v[10:11], s[0:1], 0, v[8:9]
	v_ashrrev_i32_e32 v13, 31, v12
	s_movk_i32 s0, 0x1000
	v_lshlrev_b64 v[12:13], 1, v[12:13]
	v_add_co_u32_e32 v2, vcc, s0, v2
	v_lshl_add_u64 v[10:11], v[10:11], 0, v[12:13]
	s_nop 0
	v_addc_co_u32_e32 v3, vcc, 0, v3, vcc
	v_lshl_add_u64 v[10:11], v[10:11], 0, v[32:33]
	global_load_dwordx4 v[120:123], v[2:3], off
	global_load_dwordx4 v[116:119], v[10:11], off
	v_ashrrev_i32_e32 v157, 7, v1
	v_lshlrev_b32_e32 v0, 2, v0
	v_mul_lo_u32 v1, v14, s68
	v_or_b32_e32 v12, v12, v32
	v_readlane_b32 s0, v255, 47
	v_add_u32_e32 v191, v157, v0
	v_add3_u32 v190, 0, v32, v1
	v_or_b32_e32 v192, 3, v0
	v_lshl_add_u64 v[0:1], v[12:13], 0, v[8:9]
	v_readlane_b32 s1, v255, 48
	v_add_u16_e32 v2, -1, v6
	v_and_b32_e32 v2, 3, v2
	v_lshl_add_u64 v[136:137], s[0:1], 0, v[0:1]
	v_mad_i64_i32 v[0:1], s[0:1], v14, s82, 0
	s_mov_b32 s0, 0x6880000
	s_nop 0
	v_mad_u64_u32 v[0:1], s[0:1], v4, s0, v[0:1]
	v_lshlrev_b32_e32 v2, 7, v2
	v_mov_b32_e32 v3, v33
	v_lshl_add_u64 v[0:1], v[0:1], 0, v[2:3]
	v_readlane_b32 s0, v255, 49
	v_lshl_add_u64 v[0:1], v[0:1], 0, v[32:33]
	v_readlane_b32 s1, v255, 50
	v_mov_b32_e32 v14, v33
	v_mov_b32_e32 v15, v33
	v_lshlrev_b32_e32 v46, 6, v5
	v_mul_u32_u24_e32 v155, 0x90, v7
	v_lshl_add_u64 v[138:139], s[0:1], 0, v[0:1]
	v_mov_b32_e32 v32, v33
	v_mov_b32_e32 v0, v33
	v_mov_b32_e32 v1, v33
	v_mov_b32_e32 v2, v33
	v_mov_b32_e32 v4, v33
	v_mov_b32_e32 v5, v33
	v_mov_b32_e32 v6, v33
	v_mov_b32_e32 v7, v33
	v_mov_b32_e32 v8, v33
	v_mov_b32_e32 v10, v33
	v_mov_b32_e32 v11, v33
	v_mov_b32_e32 v12, v33
	v_mov_b32_e32 v13, v33
	v_mov_b64_e32 v[78:79], v[14:15]
	v_mov_b64_e32 v[30:31], v[14:15]
	v_mov_b64_e32 v[94:95], v[14:15]
	s_mov_b32 s4, 0
	v_add_u32_e32 v133, 0, v132
	s_mov_b64 s[0:1], 0
	v_mov_b64_e32 v[76:77], v[12:13]
	v_mov_b64_e32 v[74:75], v[10:11]
	v_mov_b64_e32 v[72:73], v[8:9]
	v_mov_b64_e32 v[70:71], v[6:7]
	v_mov_b64_e32 v[68:69], v[4:5]
	v_mov_b64_e32 v[66:67], v[2:3]
	v_mov_b64_e32 v[64:65], v[0:1]
	v_mov_b64_e32 v[28:29], v[12:13]
	v_mov_b64_e32 v[26:27], v[10:11]
	v_mov_b64_e32 v[24:25], v[8:9]
	v_mov_b64_e32 v[22:23], v[6:7]
	v_mov_b64_e32 v[20:21], v[4:5]
	v_mov_b64_e32 v[18:19], v[2:3]
	v_mov_b64_e32 v[16:17], v[0:1]
	v_mov_b64_e32 v[92:93], v[12:13]
	v_mov_b64_e32 v[90:91], v[10:11]
	v_mov_b64_e32 v[88:89], v[8:9]
	v_mov_b64_e32 v[86:87], v[6:7]
	v_mov_b64_e32 v[84:85], v[4:5]
	v_mov_b64_e32 v[82:83], v[2:3]
	v_mov_b64_e32 v[80:81], v[0:1]
	v_mov_b64_e32 v[140:141], v[32:33]
	v_readfirstlane_b32 s5, v191
	v_readfirstlane_b32 s8, v192
	v_readfirstlane_b32 s2, v138
	v_readfirstlane_b32 s3, v139
	v_readfirstlane_b32 s10, v136
	v_readfirstlane_b32 s11, v137
	v_readfirstlane_b32 s0, v156
	s_nop 3
	s_lshr_b32 s1, s0, 8
	v_and_b32_e32 v204, 7, v156
	v_bfe_u32 v205, v156, 4, 3
	v_xor_b32_e32 v205, v204, v205
	v_sub_u32_e32 v206, v205, v204
	v_lshlrev_b32_e32 v206, 4, v206
	v_subrev_u32_e32 v32, s2, v138
	v_subrev_u32_e32 v157, s10, v136
	v_add_u32_e32 v32, v32, v206
	v_add_u32_e32 v157, v157, v206
	v_lshrrev_b32_e32 v207, 3, v156
	v_lshlrev_b32_e32 v207, 7, v207
	v_lshl_add_u32 v207, v205, 4, v207
	v_and_b32_e32 v204, 31, v156
	v_bfe_u32 v205, v156, 5, 1
	v_bfe_u32 v206, v156, 1, 3
	v_lshlrev_b32_e32 v204, 7, v204
	v_add_u32_e32 v146, 0, v205
	v_xor_b32_e32 v146, v146, v206
	v_lshl_add_u32 v146, v146, 4, v204
	v_add_u32_e32 v147, 2, v205
	v_xor_b32_e32 v147, v147, v206
	v_lshl_add_u32 v147, v147, 4, v204
	v_add_u32_e32 v148, 4, v205
	v_xor_b32_e32 v148, v148, v206
	v_lshl_add_u32 v148, v148, 4, v204
	v_add_u32_e32 v149, 6, v205
	v_xor_b32_e32 v149, v149, v206
	v_lshl_add_u32 v149, v149, 4, v204
	s_lshr_b32 s0, s0, 6
	s_lshl_b32 s0, s0, 10
	s_add_i32 m0, s0, 16384
	s_add_i32 s4, s4, 1
	global_load_lds_dwordx4 v32, s[2:3]
	s_add_i32 m0, s0, 24576
	s_add_u32 s2, s2, 0x68800
	s_addc_u32 s3, s3, 0
	global_load_lds_dwordx4 v157, s[10:11]
	s_add_u32 s10, s10, 0x2000
	s_addc_u32 s11, s11, 0
	s_waitcnt vmcnt(2)
	ds_write_b128 v207, v[120:123]
	ds_write_b128 v207, v[116:119] offset:8192
	s_waitcnt vmcnt(0) lgkmcnt(0)
	s_barrier
	ds_read_b128 v[166:169], v146
	ds_read_b128 v[170:173], v147
	v_mov_b32_e32 v158, 0
	v_mov_b32_e32 v159, 0
	v_mov_b32_e32 v160, 0
	v_mov_b32_e32 v161, 0
	v_mov_b32_e32 v162, 0
	v_mov_b32_e32 v163, 0
	v_mov_b32_e32 v164, 0
	v_mov_b32_e32 v165, 0
	v_mov_b32_e32 v150, 0
	v_mov_b32_e32 v151, 0
	s_mov_b32 s4, 0
	s_waitcnt lgkmcnt(0)
	v_mfma_f32_32x32x16_bf16 v[96:111], v[166:169], v[112:115], v[48:63]
	v_mfma_f32_32x32x16_bf16 v[96:111], v[170:173], v[42:45], v[96:111]
	ds_read_b128 v[166:169], v148
	ds_read_b128 v[170:173], v149
	v_mov_b32_e32 v174, 0
	v_mov_b32_e32 v175, 0
	v_mov_b32_e32 v176, 0
	v_mov_b32_e32 v177, 0
	v_mov_b32_e32 v178, 0
	v_mov_b32_e32 v179, 0
	v_mov_b32_e32 v180, 0
	v_mov_b32_e32 v181, 0
	v_mov_b32_e32 v182, 0
	v_mov_b32_e32 v183, 0
	v_mov_b32_e32 v184, 0
	v_mov_b32_e32 v185, 0
	v_mov_b32_e32 v186, 0
	v_mov_b32_e32 v187, 0
	v_mov_b32_e32 v188, 0
	v_mov_b32_e32 v189, 0
; DI float ex2(float x) { return __builtin_amdgcn_exp2f(x); }
; #define MFMA32(a, b, c) __builtin_amdgcn_mfma_f32_32x32x16_bf16((a), (b), (c), 0, 0, 0)
; template <int MODE>
; DI void attn_unit(unsigned char* lds, const AttnParams& ap, int b, int h, int qb, int tid) {
;     ...
;     if (MODE == 1) {
; #pragma unroll
;       for (int kh = 0; kh < 2; ++kh) {
;         const bf16_t* kb = Ks + (32 * kh + r32) * 72 + 8 * hi;
;         bf16x8 p0[2], p1[2];
;         { f32x16 s0 = splat16(ap.negM);
;           s0 = MFMA32(*(const bf16x8*)(kb), qf[0], s0); s0 = MFMA32(*(const bf16x8*)(kb + 16), qf[1], s0);
; #pragma unroll
;           for (int i = 0; i < 16; ++i) { s0[i] = ex2(s0[i]); l0 += s0[i]; }
;           p0[0] = pack8(s0, 0); p0[1] = pack8(s0, 1); }
;         { f32x16 s1 = splat16(ap.negM);
;           s1 = MFMA32(*(const bf16x8*)(kb + 32), qf[2], s1); s1 = MFMA32(*(const bf16x8*)(kb + 48), qf[3], s1);
; #pragma unroll
;           for (int i = 0; i < 16; ++i) { s1[i] = ex2(s1[i]); l1 += s1[i]; }
;           p1[0] = pack8(s1, 0); p1[1] = pack8(s1, 1); }
; #pragma unroll
;         for (int kk = 0; kk < 2; ++kk) {
; #pragma unroll
;           for (int eb = 0; eb < 2; ++eb) { const bf16_t* vb = Vs + (32 * eb + r32) * 72 + 32 * kh + 16 * kk + 8 * hi; const bf16x8 vf = *(const bf16x8*)vb;
;             O0[eb] = MFMA32(vf, p0[kk], O0[eb]); O1[eb] = MFMA32(vf, p1[kk], O1[eb]); } }
;       }
.Lc_tile_ph0:
	s_add_i32 m0, s0, 32768
	s_add_i32 s4, s4, 1
	global_load_lds_dwordx4 v32, s[2:3]
	s_add_i32 m0, s0, 40960
	s_add_u32 s2, s2, 0x68800
	s_addc_u32 s3, s3, 0
	global_load_lds_dwordx4 v157, s[10:11]
	s_add_u32 s10, s10, 0x2000
	s_addc_u32 s11, s11, 0
	s_cmp_lg_u32 s1, 0
	s_cbranch_scc1 .Lc_nodly0
	s_nop 15
	s_nop 15
.Lc_nodly0:
	s_waitcnt lgkmcnt(0)
	v_mfma_f32_32x32x16_bf16 v[116:131], v[166:169], v[38:41], v[48:63]
	v_exp_f32_e32 v96, v96
	v_exp_f32_e32 v97, v97
	v_exp_f32_e32 v98, v98
	v_exp_f32_e32 v99, v99
	v_mfma_f32_32x32x16_bf16 v[116:131], v[170:173], v[34:37], v[116:131]
	v_exp_f32_e32 v100, v100
	v_exp_f32_e32 v101, v101
	v_exp_f32_e32 v102, v102
	v_exp_f32_e32 v103, v103
	ds_read_b128 v[166:169], v146 offset:4096
	ds_read_b128 v[170:173], v147 offset:4096
	v_mfma_f32_32x32x16_bf16 v[80:95], v[174:177], v[158:161], v[80:95]
	v_exp_f32_e32 v104, v104
	v_exp_f32_e32 v105, v105
	v_add_f32_e32 v141, v141, v96
	v_add_f32_e32 v150, v150, v97
	v_add_f32_e32 v141, v141, v98
	v_add_f32_e32 v150, v150, v99
	v_mfma_f32_32x32x16_bf16 v[16:31], v[182:185], v[158:161], v[16:31]
	v_exp_f32_e32 v106, v106
	v_exp_f32_e32 v107, v107
	v_cvt_pk_bf16_f32 v158, v96, v97
	v_cvt_pk_bf16_f32 v159, v98, v99
	v_add_f32_e32 v141, v141, v100
	v_add_f32_e32 v150, v150, v101
	v_mfma_f32_32x32x16_bf16 v[80:95], v[178:181], v[162:165], v[80:95]
	v_exp_f32_e32 v108, v108
	v_exp_f32_e32 v109, v109
	v_cvt_pk_bf16_f32 v160, v100, v101
	v_cvt_pk_bf16_f32 v161, v102, v103
	v_add_f32_e32 v141, v141, v102
	v_add_f32_e32 v150, v150, v103
	v_mfma_f32_32x32x16_bf16 v[16:31], v[186:189], v[162:165], v[16:31]
	ds_read_b128 v[174:177], v146 offset:8192
	ds_read_b128 v[178:181], v147 offset:8192
	ds_read_b128 v[182:185], v146 offset:12288
	ds_read_b128 v[186:189], v147 offset:12288
	v_exp_f32_e32 v110, v110
	v_exp_f32_e32 v111, v111
	v_add_f32_e32 v141, v141, v104
	v_add_f32_e32 v150, v150, v105
	v_add_f32_e32 v141, v141, v106
	v_add_f32_e32 v150, v150, v107
	v_add_f32_e32 v141, v141, v108
	v_add_f32_e32 v150, v150, v109
	v_cvt_pk_bf16_f32 v162, v104, v105
	v_cvt_pk_bf16_f32 v163, v106, v107
	v_cvt_pk_bf16_f32 v164, v108, v109
	v_add_f32_e32 v141, v141, v110
	v_add_f32_e32 v150, v150, v111
	v_cvt_pk_bf16_f32 v165, v110, v111
	s_waitcnt lgkmcnt(4)
	v_mfma_f32_32x32x16_bf16 v[96:111], v[166:169], v[112:115], v[48:63]
	v_exp_f32_e32 v116, v116
	v_exp_f32_e32 v117, v117
	v_exp_f32_e32 v118, v118
	v_exp_f32_e32 v119, v119
	v_mfma_f32_32x32x16_bf16 v[96:111], v[170:173], v[42:45], v[96:111]
	v_exp_f32_e32 v120, v120
	v_exp_f32_e32 v121, v121
	v_exp_f32_e32 v122, v122
	v_exp_f32_e32 v123, v123
	ds_read_b128 v[166:169], v148 offset:4096
	ds_read_b128 v[170:173], v149 offset:4096
	s_waitcnt lgkmcnt(2)
	v_mfma_f32_32x32x16_bf16 v[64:79], v[174:177], v[158:161], v[64:79]
	v_exp_f32_e32 v124, v124
	v_exp_f32_e32 v125, v125
	v_add_f32_e32 v140, v140, v116
	v_add_f32_e32 v151, v151, v117
	v_add_f32_e32 v140, v140, v118
	v_add_f32_e32 v151, v151, v119
	v_mfma_f32_32x32x16_bf16 v[0:15], v[182:185], v[158:161], v[0:15]
	v_exp_f32_e32 v126, v126
	v_exp_f32_e32 v127, v127
	v_cvt_pk_bf16_f32 v158, v116, v117
	v_cvt_pk_bf16_f32 v159, v118, v119
	v_add_f32_e32 v140, v140, v120
	v_add_f32_e32 v151, v151, v121
	v_mfma_f32_32x32x16_bf16 v[64:79], v[178:181], v[162:165], v[64:79]
	v_exp_f32_e32 v128, v128
	v_exp_f32_e32 v129, v129
	v_cvt_pk_bf16_f32 v160, v120, v121
	v_cvt_pk_bf16_f32 v161, v122, v123
	v_add_f32_e32 v140, v140, v122
	v_add_f32_e32 v151, v151, v123
	v_mfma_f32_32x32x16_bf16 v[0:15], v[186:189], v[162:165], v[0:15]
	v_exp_f32_e32 v130, v130
	v_exp_f32_e32 v131, v131
	v_add_f32_e32 v140, v140, v124
	v_add_f32_e32 v151, v151, v125
	v_add_f32_e32 v140, v140, v126
	v_add_f32_e32 v151, v151, v127
	v_add_f32_e32 v140, v140, v128
	v_add_f32_e32 v151, v151, v129
	v_cvt_pk_bf16_f32 v162, v124, v125
	v_cvt_pk_bf16_f32 v163, v126, v127
	v_cvt_pk_bf16_f32 v164, v128, v129
	v_add_f32_e32 v140, v140, v130
	v_add_f32_e32 v151, v151, v131
	v_cvt_pk_bf16_f32 v165, v130, v131
	s_waitcnt lgkmcnt(0)
	v_mfma_f32_32x32x16_bf16 v[116:131], v[166:169], v[38:41], v[48:63]
	v_exp_f32_e32 v96, v96
	v_exp_f32_e32 v97, v97
	v_exp_f32_e32 v98, v98
	v_exp_f32_e32 v99, v99
	v_mfma_f32_32x32x16_bf16 v[116:131], v[170:173], v[34:37], v[116:131]
	v_exp_f32_e32 v100, v100
	v_exp_f32_e32 v101, v101
	v_exp_f32_e32 v102, v102
	v_exp_f32_e32 v103, v103
	ds_read_b128 v[166:169], v146 offset:16384
	ds_read_b128 v[170:173], v147 offset:16384
	v_mfma_f32_32x32x16_bf16 v[80:95], v[174:177], v[158:161], v[80:95]
	v_exp_f32_e32 v104, v104
	v_exp_f32_e32 v105, v105
	v_add_f32_e32 v141, v141, v96
	v_add_f32_e32 v150, v150, v97
	v_add_f32_e32 v141, v141, v98
	v_add_f32_e32 v150, v150, v99
	v_mfma_f32_32x32x16_bf16 v[16:31], v[182:185], v[158:161], v[16:31]
	v_exp_f32_e32 v106, v106
	v_exp_f32_e32 v107, v107
	v_cvt_pk_bf16_f32 v158, v96, v97
	v_cvt_pk_bf16_f32 v159, v98, v99
	v_add_f32_e32 v141, v141, v100
	v_add_f32_e32 v150, v150, v101
	v_mfma_f32_32x32x16_bf16 v[80:95], v[178:181], v[162:165], v[80:95]
	v_exp_f32_e32 v108, v108
	v_exp_f32_e32 v109, v109
	v_cvt_pk_bf16_f32 v160, v100, v101
	v_cvt_pk_bf16_f32 v161, v102, v103
	v_add_f32_e32 v141, v141, v102
	v_add_f32_e32 v150, v150, v103
	v_mfma_f32_32x32x16_bf16 v[16:31], v[186:189], v[162:165], v[16:31]
	ds_read_b128 v[174:177], v148 offset:8192
	ds_read_b128 v[178:181], v149 offset:8192
	ds_read_b128 v[182:185], v148 offset:12288
	ds_read_b128 v[186:189], v149 offset:12288
	v_exp_f32_e32 v110, v110
	v_exp_f32_e32 v111, v111
	v_add_f32_e32 v141, v141, v104
	v_add_f32_e32 v150, v150, v105
	v_add_f32_e32 v141, v141, v106
	v_add_f32_e32 v150, v150, v107
	v_add_f32_e32 v141, v141, v108
	v_add_f32_e32 v150, v150, v109
	v_cvt_pk_bf16_f32 v162, v104, v105
	v_cvt_pk_bf16_f32 v163, v106, v107
	v_cvt_pk_bf16_f32 v164, v108, v109
	v_add_f32_e32 v141, v141, v110
	v_add_f32_e32 v150, v150, v111
	v_cvt_pk_bf16_f32 v165, v110, v111
	s_waitcnt lgkmcnt(4)
; DI float ex2(float x) { return __builtin_amdgcn_exp2f(x); }
; #define MFMA32(a, b, c) __builtin_amdgcn_mfma_f32_32x32x16_bf16((a), (b), (c), 0, 0, 0)
; template <int MODE>
; DI void attn_unit(unsigned char* lds, const AttnParams& ap, int b, int h, int qb, int tid) {
;     ...
;     for (int c = 0; c < NCH; ++c) { *(u32x4*)(Ks0 + (c * 64 + lrow) * 72 + 8 * lch) = kreg[c]; *(u32x4*)(Vs0 + (c * 64 + lrow) * 72 + 8 * lch) = vreg[c]; }
;     __syncthreads();
;     if (n + NCH < ntiles) {
; #pragma unroll
;       for (int c = 0; c < NCH; ++c) { const int jn = (MODE == 2) ? jb - NCH - c : jb + NCH + c; kreg[c] = *(const u32x4*)(kg + (size_t)jn * 64 * PLD); vreg[c] = *(const u32x4*)(vg + (size_t)jn * 4096); } }
;     ...
;     if (MODE == 1) {
; #pragma unroll
;       for (int kh = 0; kh < 2; ++kh) {
;         const bf16_t* kb = Ks + (32 * kh + r32) * 72 + 8 * hi;
;         bf16x8 p0[2], p1[2];
;         { f32x16 s0 = splat16(ap.negM);
;           s0 = MFMA32(*(const bf16x8*)(kb), qf[0], s0); s0 = MFMA32(*(const bf16x8*)(kb + 16), qf[1], s0);
; #pragma unroll
;           for (int i = 0; i < 16; ++i) { s0[i] = ex2(s0[i]); l0 += s0[i]; }
;           p0[0] = pack8(s0, 0); p0[1] = pack8(s0, 1); }
;         { f32x16 s1 = splat16(ap.negM);
;           s1 = MFMA32(*(const bf16x8*)(kb + 32), qf[2], s1); s1 = MFMA32(*(const bf16x8*)(kb + 48), qf[3], s1);
; #pragma unroll
;           for (int i = 0; i < 16; ++i) { s1[i] = ex2(s1[i]); l1 += s1[i]; }
;           p1[0] = pack8(s1, 0); p1[1] = pack8(s1, 1); }
; #pragma unroll
;         for (int kk = 0; kk < 2; ++kk) {
; #pragma unroll
;           for (int eb = 0; eb < 2; ++eb) { const bf16_t* vb = Vs + (32 * eb + r32) * 72 + 32 * kh + 16 * kk + 8 * hi; const bf16x8 vf = *(const bf16x8*)vb;
;             O0[eb] = MFMA32(vf, p0[kk], O0[eb]); O1[eb] = MFMA32(vf, p1[kk], O1[eb]); } }
;       }
	v_mfma_f32_32x32x16_bf16 v[96:111], v[166:169], v[112:115], v[48:63]
	v_exp_f32_e32 v116, v116
	v_exp_f32_e32 v117, v117
	v_exp_f32_e32 v118, v118
	v_exp_f32_e32 v119, v119
	v_mfma_f32_32x32x16_bf16 v[96:111], v[170:173], v[42:45], v[96:111]
	v_exp_f32_e32 v120, v120
	v_exp_f32_e32 v121, v121
	v_exp_f32_e32 v122, v122
	v_exp_f32_e32 v123, v123
	ds_read_b128 v[166:169], v148 offset:16384
	ds_read_b128 v[170:173], v149 offset:16384
	s_waitcnt lgkmcnt(2)
	v_mfma_f32_32x32x16_bf16 v[64:79], v[174:177], v[158:161], v[64:79]
	v_exp_f32_e32 v124, v124
	v_exp_f32_e32 v125, v125
	v_add_f32_e32 v140, v140, v116
	v_add_f32_e32 v151, v151, v117
	v_add_f32_e32 v140, v140, v118
	v_add_f32_e32 v151, v151, v119
	v_mfma_f32_32x32x16_bf16 v[0:15], v[182:185], v[158:161], v[0:15]
	v_exp_f32_e32 v126, v126
	v_exp_f32_e32 v127, v127
	v_cvt_pk_bf16_f32 v158, v116, v117
	v_cvt_pk_bf16_f32 v159, v118, v119
	v_add_f32_e32 v140, v140, v120
	v_add_f32_e32 v151, v151, v121
	v_mfma_f32_32x32x16_bf16 v[64:79], v[178:181], v[162:165], v[64:79]
	v_exp_f32_e32 v128, v128
	v_exp_f32_e32 v129, v129
	v_cvt_pk_bf16_f32 v160, v120, v121
	v_cvt_pk_bf16_f32 v161, v122, v123
	v_add_f32_e32 v140, v140, v122
	v_add_f32_e32 v151, v151, v123
	v_mfma_f32_32x32x16_bf16 v[0:15], v[186:189], v[162:165], v[0:15]
	v_exp_f32_e32 v130, v130
	v_exp_f32_e32 v131, v131
	v_add_f32_e32 v140, v140, v124
	v_add_f32_e32 v151, v151, v125
	v_add_f32_e32 v140, v140, v126
	v_add_f32_e32 v151, v151, v127
	v_add_f32_e32 v140, v140, v128
	v_add_f32_e32 v151, v151, v129
	v_cvt_pk_bf16_f32 v162, v124, v125
	v_cvt_pk_bf16_f32 v163, v126, v127
	v_cvt_pk_bf16_f32 v164, v128, v129
	v_add_f32_e32 v140, v140, v130
	v_add_f32_e32 v151, v151, v131
	v_cvt_pk_bf16_f32 v165, v130, v131
	s_waitcnt vmcnt(0) lgkmcnt(0)
	s_barrier
	s_cmp_le_u32 s4, s5
	s_cbranch_scc1 .Lc_tile_ph1
	s_mov_b32 s9, 1
	s_branch .Lc_drain
.Lc_tile_ph1:
	s_add_i32 m0, s0, 0
	s_add_i32 s4, s4, 1
	global_load_lds_dwordx4 v32, s[2:3]
	s_add_i32 m0, s0, 8192
	s_add_u32 s2, s2, 0x68800
	s_addc_u32 s3, s3, 0
	global_load_lds_dwordx4 v157, s[10:11]
	s_add_u32 s10, s10, 0x2000
	s_addc_u32 s11, s11, 0
	s_cmp_lg_u32 s1, 0
	s_cbranch_scc1 .Lc_nodly1
	s_nop 15
	s_nop 15
.Lc_nodly1:
	s_waitcnt lgkmcnt(0)
	v_mfma_f32_32x32x16_bf16 v[116:131], v[166:169], v[38:41], v[48:63]
	v_exp_f32_e32 v96, v96
	v_exp_f32_e32 v97, v97
	v_exp_f32_e32 v98, v98
	v_exp_f32_e32 v99, v99
	v_mfma_f32_32x32x16_bf16 v[116:131], v[170:173], v[34:37], v[116:131]
	v_exp_f32_e32 v100, v100
	v_exp_f32_e32 v101, v101
	v_exp_f32_e32 v102, v102
	v_exp_f32_e32 v103, v103
	ds_read_b128 v[166:169], v146 offset:20480
	ds_read_b128 v[170:173], v147 offset:20480
	v_mfma_f32_32x32x16_bf16 v[80:95], v[174:177], v[158:161], v[80:95]
	v_exp_f32_e32 v104, v104
	v_exp_f32_e32 v105, v105
	v_add_f32_e32 v141, v141, v96
	v_add_f32_e32 v150, v150, v97
	v_add_f32_e32 v141, v141, v98
	v_add_f32_e32 v150, v150, v99
	v_mfma_f32_32x32x16_bf16 v[16:31], v[182:185], v[158:161], v[16:31]
	v_exp_f32_e32 v106, v106
	v_exp_f32_e32 v107, v107
	v_cvt_pk_bf16_f32 v158, v96, v97
	v_cvt_pk_bf16_f32 v159, v98, v99
	v_add_f32_e32 v141, v141, v100
	v_add_f32_e32 v150, v150, v101
	v_mfma_f32_32x32x16_bf16 v[80:95], v[178:181], v[162:165], v[80:95]
	v_exp_f32_e32 v108, v108
	v_exp_f32_e32 v109, v109
	v_cvt_pk_bf16_f32 v160, v100, v101
	v_cvt_pk_bf16_f32 v161, v102, v103
	v_add_f32_e32 v141, v141, v102
	v_add_f32_e32 v150, v150, v103
	v_mfma_f32_32x32x16_bf16 v[16:31], v[186:189], v[162:165], v[16:31]
	ds_read_b128 v[174:177], v146 offset:24576
	ds_read_b128 v[178:181], v147 offset:24576
	ds_read_b128 v[182:185], v146 offset:28672
	ds_read_b128 v[186:189], v147 offset:28672
	v_exp_f32_e32 v110, v110
	v_exp_f32_e32 v111, v111
	v_add_f32_e32 v141, v141, v104
	v_add_f32_e32 v150, v150, v105
	v_add_f32_e32 v141, v141, v106
	v_add_f32_e32 v150, v150, v107
	v_add_f32_e32 v141, v141, v108
	v_add_f32_e32 v150, v150, v109
	v_cvt_pk_bf16_f32 v162, v104, v105
	v_cvt_pk_bf16_f32 v163, v106, v107
	v_cvt_pk_bf16_f32 v164, v108, v109
	v_add_f32_e32 v141, v141, v110
	v_add_f32_e32 v150, v150, v111
	v_cvt_pk_bf16_f32 v165, v110, v111
	s_waitcnt lgkmcnt(4)
	v_mfma_f32_32x32x16_bf16 v[96:111], v[166:169], v[112:115], v[48:63]
	v_exp_f32_e32 v116, v116
	v_exp_f32_e32 v117, v117
	v_exp_f32_e32 v118, v118
	v_exp_f32_e32 v119, v119
	v_mfma_f32_32x32x16_bf16 v[96:111], v[170:173], v[42:45], v[96:111]
	v_exp_f32_e32 v120, v120
	v_exp_f32_e32 v121, v121
	v_exp_f32_e32 v122, v122
	v_exp_f32_e32 v123, v123
	ds_read_b128 v[166:169], v148 offset:20480
	ds_read_b128 v[170:173], v149 offset:20480
	s_waitcnt lgkmcnt(2)
	v_mfma_f32_32x32x16_bf16 v[64:79], v[174:177], v[158:161], v[64:79]
	v_exp_f32_e32 v124, v124
	v_exp_f32_e32 v125, v125
	v_add_f32_e32 v140, v140, v116
	v_add_f32_e32 v151, v151, v117
	v_add_f32_e32 v140, v140, v118
	v_add_f32_e32 v151, v151, v119
	v_mfma_f32_32x32x16_bf16 v[0:15], v[182:185], v[158:161], v[0:15]
	v_exp_f32_e32 v126, v126
	v_exp_f32_e32 v127, v127
	v_cvt_pk_bf16_f32 v158, v116, v117
	v_cvt_pk_bf16_f32 v159, v118, v119
	v_add_f32_e32 v140, v140, v120
	v_add_f32_e32 v151, v151, v121
	v_mfma_f32_32x32x16_bf16 v[64:79], v[178:181], v[162:165], v[64:79]
	v_exp_f32_e32 v128, v128
	v_exp_f32_e32 v129, v129
	v_cvt_pk_bf16_f32 v160, v120, v121
	v_cvt_pk_bf16_f32 v161, v122, v123
	v_add_f32_e32 v140, v140, v122
	v_add_f32_e32 v151, v151, v123
	v_mfma_f32_32x32x16_bf16 v[0:15], v[186:189], v[162:165], v[0:15]
	v_exp_f32_e32 v130, v130
	v_exp_f32_e32 v131, v131
	v_add_f32_e32 v140, v140, v124
	v_add_f32_e32 v151, v151, v125
	v_add_f32_e32 v140, v140, v126
	v_add_f32_e32 v151, v151, v127
	v_add_f32_e32 v140, v140, v128
	v_add_f32_e32 v151, v151, v129
	v_cvt_pk_bf16_f32 v162, v124, v125
	v_cvt_pk_bf16_f32 v163, v126, v127
	v_cvt_pk_bf16_f32 v164, v128, v129
	v_add_f32_e32 v140, v140, v130
	v_add_f32_e32 v151, v151, v131
	v_cvt_pk_bf16_f32 v165, v130, v131
	s_waitcnt lgkmcnt(0)
; DI float ex2(float x) { return __builtin_amdgcn_exp2f(x); }
; #define MFMA32(a, b, c) __builtin_amdgcn_mfma_f32_32x32x16_bf16((a), (b), (c), 0, 0, 0)
; template <int MODE>
; DI void attn_unit(unsigned char* lds, const AttnParams& ap, int b, int h, int qb, int tid) {
;     ...
;     for (int c = 0; c < NCH; ++c) { *(u32x4*)(Ks0 + (c * 64 + lrow) * 72 + 8 * lch) = kreg[c]; *(u32x4*)(Vs0 + (c * 64 + lrow) * 72 + 8 * lch) = vreg[c]; }
;     __syncthreads();
;     if (n + NCH < ntiles) {
; #pragma unroll
;       for (int c = 0; c < NCH; ++c) { const int jn = (MODE == 2) ? jb - NCH - c : jb + NCH + c; kreg[c] = *(const u32x4*)(kg + (size_t)jn * 64 * PLD); vreg[c] = *(const u32x4*)(vg + (size_t)jn * 4096); } }
;     ...
;     if (MODE == 1) {
; #pragma unroll
;       for (int kh = 0; kh < 2; ++kh) {
;         const bf16_t* kb = Ks + (32 * kh + r32) * 72 + 8 * hi;
;         bf16x8 p0[2], p1[2];
;         { f32x16 s0 = splat16(ap.negM);
;           s0 = MFMA32(*(const bf16x8*)(kb), qf[0], s0); s0 = MFMA32(*(const bf16x8*)(kb + 16), qf[1], s0);
; #pragma unroll
;           for (int i = 0; i < 16; ++i) { s0[i] = ex2(s0[i]); l0 += s0[i]; }
;           p0[0] = pack8(s0, 0); p0[1] = pack8(s0, 1); }
;         { f32x16 s1 = splat16(ap.negM);
;           s1 = MFMA32(*(const bf16x8*)(kb + 32), qf[2], s1); s1 = MFMA32(*(const bf16x8*)(kb + 48), qf[3], s1);
; #pragma unroll
;           for (int i = 0; i < 16; ++i) { s1[i] = ex2(s1[i]); l1 += s1[i]; }
;           p1[0] = pack8(s1, 0); p1[1] = pack8(s1, 1); }
; #pragma unroll
;         for (int kk = 0; kk < 2; ++kk) {
; #pragma unroll
;           for (int eb = 0; eb < 2; ++eb) { const bf16_t* vb = Vs + (32 * eb + r32) * 72 + 32 * kh + 16 * kk + 8 * hi; const bf16x8 vf = *(const bf16x8*)vb;
;             O0[eb] = MFMA32(vf, p0[kk], O0[eb]); O1[eb] = MFMA32(vf, p1[kk], O1[eb]); } }
;       }
	v_mfma_f32_32x32x16_bf16 v[116:131], v[166:169], v[38:41], v[48:63]
	v_exp_f32_e32 v96, v96
	v_exp_f32_e32 v97, v97
	v_exp_f32_e32 v98, v98
	v_exp_f32_e32 v99, v99
	v_mfma_f32_32x32x16_bf16 v[116:131], v[170:173], v[34:37], v[116:131]
	v_exp_f32_e32 v100, v100
	v_exp_f32_e32 v101, v101
	v_exp_f32_e32 v102, v102
	v_exp_f32_e32 v103, v103
	ds_read_b128 v[166:169], v146 offset:32768
	ds_read_b128 v[170:173], v147 offset:32768
	v_mfma_f32_32x32x16_bf16 v[80:95], v[174:177], v[158:161], v[80:95]
	v_exp_f32_e32 v104, v104
	v_exp_f32_e32 v105, v105
	v_add_f32_e32 v141, v141, v96
	v_add_f32_e32 v150, v150, v97
	v_add_f32_e32 v141, v141, v98
	v_add_f32_e32 v150, v150, v99
	v_mfma_f32_32x32x16_bf16 v[16:31], v[182:185], v[158:161], v[16:31]
	v_exp_f32_e32 v106, v106
	v_exp_f32_e32 v107, v107
	v_cvt_pk_bf16_f32 v158, v96, v97
	v_cvt_pk_bf16_f32 v159, v98, v99
	v_add_f32_e32 v141, v141, v100
	v_add_f32_e32 v150, v150, v101
	v_mfma_f32_32x32x16_bf16 v[80:95], v[178:181], v[162:165], v[80:95]
	v_exp_f32_e32 v108, v108
	v_exp_f32_e32 v109, v109
	v_cvt_pk_bf16_f32 v160, v100, v101
	v_cvt_pk_bf16_f32 v161, v102, v103
	v_add_f32_e32 v141, v141, v102
	v_add_f32_e32 v150, v150, v103
	v_mfma_f32_32x32x16_bf16 v[16:31], v[186:189], v[162:165], v[16:31]
	ds_read_b128 v[174:177], v148 offset:24576
	ds_read_b128 v[178:181], v149 offset:24576
	ds_read_b128 v[182:185], v148 offset:28672
	ds_read_b128 v[186:189], v149 offset:28672
	v_exp_f32_e32 v110, v110
	v_exp_f32_e32 v111, v111
	v_add_f32_e32 v141, v141, v104
	v_add_f32_e32 v150, v150, v105
	v_add_f32_e32 v141, v141, v106
	v_add_f32_e32 v150, v150, v107
	v_add_f32_e32 v141, v141, v108
	v_add_f32_e32 v150, v150, v109
	v_cvt_pk_bf16_f32 v162, v104, v105
	v_cvt_pk_bf16_f32 v163, v106, v107
	v_cvt_pk_bf16_f32 v164, v108, v109
	v_add_f32_e32 v141, v141, v110
	v_add_f32_e32 v150, v150, v111
	v_cvt_pk_bf16_f32 v165, v110, v111
	s_waitcnt lgkmcnt(4)
	v_mfma_f32_32x32x16_bf16 v[96:111], v[166:169], v[112:115], v[48:63]
	v_exp_f32_e32 v116, v116
	v_exp_f32_e32 v117, v117
	v_exp_f32_e32 v118, v118
	v_exp_f32_e32 v119, v119
	v_mfma_f32_32x32x16_bf16 v[96:111], v[170:173], v[42:45], v[96:111]
	v_exp_f32_e32 v120, v120
	v_exp_f32_e32 v121, v121
	v_exp_f32_e32 v122, v122
	v_exp_f32_e32 v123, v123
	ds_read_b128 v[166:169], v148 offset:32768
	ds_read_b128 v[170:173], v149 offset:32768
	s_waitcnt lgkmcnt(2)
	v_mfma_f32_32x32x16_bf16 v[64:79], v[174:177], v[158:161], v[64:79]
	v_exp_f32_e32 v124, v124
	v_exp_f32_e32 v125, v125
	v_add_f32_e32 v140, v140, v116
	v_add_f32_e32 v151, v151, v117
	v_add_f32_e32 v140, v140, v118
	v_add_f32_e32 v151, v151, v119
	v_mfma_f32_32x32x16_bf16 v[0:15], v[182:185], v[158:161], v[0:15]
	v_exp_f32_e32 v126, v126
	v_exp_f32_e32 v127, v127
	v_cvt_pk_bf16_f32 v158, v116, v117
	v_cvt_pk_bf16_f32 v159, v118, v119
	v_add_f32_e32 v140, v140, v120
	v_add_f32_e32 v151, v151, v121
	v_mfma_f32_32x32x16_bf16 v[64:79], v[178:181], v[162:165], v[64:79]
	v_exp_f32_e32 v128, v128
	v_exp_f32_e32 v129, v129
	v_cvt_pk_bf16_f32 v160, v120, v121
	v_cvt_pk_bf16_f32 v161, v122, v123
	v_add_f32_e32 v140, v140, v122
	v_add_f32_e32 v151, v151, v123
	v_mfma_f32_32x32x16_bf16 v[0:15], v[186:189], v[162:165], v[0:15]
	v_exp_f32_e32 v130, v130
	v_exp_f32_e32 v131, v131
	v_add_f32_e32 v140, v140, v124
	v_add_f32_e32 v151, v151, v125
	v_add_f32_e32 v140, v140, v126
	v_add_f32_e32 v151, v151, v127
	v_add_f32_e32 v140, v140, v128
	v_add_f32_e32 v151, v151, v129
	v_cvt_pk_bf16_f32 v162, v124, v125
	v_cvt_pk_bf16_f32 v163, v126, v127
	v_cvt_pk_bf16_f32 v164, v128, v129
	v_add_f32_e32 v140, v140, v130
	v_add_f32_e32 v151, v151, v131
	v_cvt_pk_bf16_f32 v165, v130, v131
	s_waitcnt vmcnt(0) lgkmcnt(0)
	s_barrier
	s_cmp_le_u32 s4, s5
	s_cbranch_scc1 .Lc_tile_ph2
	s_mov_b32 s9, 2
	s_branch .Lc_drain
.Lc_tile_ph2:
	s_add_i32 m0, s0, 16384
	s_add_i32 s4, s4, 1
	global_load_lds_dwordx4 v32, s[2:3]
	s_add_i32 m0, s0, 24576
	s_add_u32 s2, s2, 0x68800
	s_addc_u32 s3, s3, 0
	global_load_lds_dwordx4 v157, s[10:11]
	s_add_u32 s10, s10, 0x2000
	s_addc_u32 s11, s11, 0
	s_cmp_lg_u32 s1, 0
	s_cbranch_scc1 .Lc_nodly2
	s_nop 15
	s_nop 15
.Lc_nodly2:
	s_waitcnt lgkmcnt(0)
	v_mfma_f32_32x32x16_bf16 v[116:131], v[166:169], v[38:41], v[48:63]
	v_exp_f32_e32 v96, v96
	v_exp_f32_e32 v97, v97
	v_exp_f32_e32 v98, v98
	v_exp_f32_e32 v99, v99
	v_mfma_f32_32x32x16_bf16 v[116:131], v[170:173], v[34:37], v[116:131]
	v_exp_f32_e32 v100, v100
	v_exp_f32_e32 v101, v101
	v_exp_f32_e32 v102, v102
	v_exp_f32_e32 v103, v103
	ds_read_b128 v[166:169], v146 offset:36864
	ds_read_b128 v[170:173], v147 offset:36864
	v_mfma_f32_32x32x16_bf16 v[80:95], v[174:177], v[158:161], v[80:95]
	v_exp_f32_e32 v104, v104
	v_exp_f32_e32 v105, v105
	v_add_f32_e32 v141, v141, v96
	v_add_f32_e32 v150, v150, v97
	v_add_f32_e32 v141, v141, v98
	v_add_f32_e32 v150, v150, v99
	v_mfma_f32_32x32x16_bf16 v[16:31], v[182:185], v[158:161], v[16:31]
	v_exp_f32_e32 v106, v106
	v_exp_f32_e32 v107, v107
	v_cvt_pk_bf16_f32 v158, v96, v97
	v_cvt_pk_bf16_f32 v159, v98, v99
	v_add_f32_e32 v141, v141, v100
	v_add_f32_e32 v150, v150, v101
	v_mfma_f32_32x32x16_bf16 v[80:95], v[178:181], v[162:165], v[80:95]
	v_exp_f32_e32 v108, v108
	v_exp_f32_e32 v109, v109
	v_cvt_pk_bf16_f32 v160, v100, v101
	v_cvt_pk_bf16_f32 v161, v102, v103
	v_add_f32_e32 v141, v141, v102
	v_add_f32_e32 v150, v150, v103
	v_mfma_f32_32x32x16_bf16 v[16:31], v[186:189], v[162:165], v[16:31]
	ds_read_b128 v[174:177], v146 offset:40960
	ds_read_b128 v[178:181], v147 offset:40960
	ds_read_b128 v[182:185], v146 offset:45056
	ds_read_b128 v[186:189], v147 offset:45056
	v_exp_f32_e32 v110, v110
	v_exp_f32_e32 v111, v111
	v_add_f32_e32 v141, v141, v104
	v_add_f32_e32 v150, v150, v105
	v_add_f32_e32 v141, v141, v106
	v_add_f32_e32 v150, v150, v107
	v_add_f32_e32 v141, v141, v108
	v_add_f32_e32 v150, v150, v109
	v_cvt_pk_bf16_f32 v162, v104, v105
	v_cvt_pk_bf16_f32 v163, v106, v107
	v_cvt_pk_bf16_f32 v164, v108, v109
	v_add_f32_e32 v141, v141, v110
	v_add_f32_e32 v150, v150, v111
	v_cvt_pk_bf16_f32 v165, v110, v111
	s_waitcnt lgkmcnt(4)
; DI float ex2(float x) { return __builtin_amdgcn_exp2f(x); }
; #define MFMA32(a, b, c) __builtin_amdgcn_mfma_f32_32x32x16_bf16((a), (b), (c), 0, 0, 0)
; template <int MODE>
; DI void attn_unit(unsigned char* lds, const AttnParams& ap, int b, int h, int qb, int tid) {
;     ...
;     if (MODE == 1) {
; #pragma unroll
;       for (int kh = 0; kh < 2; ++kh) {
;         const bf16_t* kb = Ks + (32 * kh + r32) * 72 + 8 * hi;
;         bf16x8 p0[2], p1[2];
;         { f32x16 s0 = splat16(ap.negM);
;           s0 = MFMA32(*(const bf16x8*)(kb), qf[0], s0); s0 = MFMA32(*(const bf16x8*)(kb + 16), qf[1], s0);
; #pragma unroll
;           for (int i = 0; i < 16; ++i) { s0[i] = ex2(s0[i]); l0 += s0[i]; }
;           p0[0] = pack8(s0, 0); p0[1] = pack8(s0, 1); }
;         { f32x16 s1 = splat16(ap.negM);
;           s1 = MFMA32(*(const bf16x8*)(kb + 32), qf[2], s1); s1 = MFMA32(*(const bf16x8*)(kb + 48), qf[3], s1);
; #pragma unroll
;           for (int i = 0; i < 16; ++i) { s1[i] = ex2(s1[i]); l1 += s1[i]; }
;           p1[0] = pack8(s1, 0); p1[1] = pack8(s1, 1); }
; #pragma unroll
;         for (int kk = 0; kk < 2; ++kk) {
; #pragma unroll
;           for (int eb = 0; eb < 2; ++eb) { const bf16_t* vb = Vs + (32 * eb + r32) * 72 + 32 * kh + 16 * kk + 8 * hi; const bf16x8 vf = *(const bf16x8*)vb;
;             O0[eb] = MFMA32(vf, p0[kk], O0[eb]); O1[eb] = MFMA32(vf, p1[kk], O1[eb]); } }
;       }
	v_mfma_f32_32x32x16_bf16 v[96:111], v[166:169], v[112:115], v[48:63]
	v_exp_f32_e32 v116, v116
	v_exp_f32_e32 v117, v117
	v_exp_f32_e32 v118, v118
	v_exp_f32_e32 v119, v119
	v_mfma_f32_32x32x16_bf16 v[96:111], v[170:173], v[42:45], v[96:111]
	v_exp_f32_e32 v120, v120
	v_exp_f32_e32 v121, v121
	v_exp_f32_e32 v122, v122
	v_exp_f32_e32 v123, v123
	ds_read_b128 v[166:169], v148 offset:36864
	ds_read_b128 v[170:173], v149 offset:36864
	s_waitcnt lgkmcnt(2)
	v_mfma_f32_32x32x16_bf16 v[64:79], v[174:177], v[158:161], v[64:79]
	v_exp_f32_e32 v124, v124
	v_exp_f32_e32 v125, v125
	v_add_f32_e32 v140, v140, v116
	v_add_f32_e32 v151, v151, v117
	v_add_f32_e32 v140, v140, v118
	v_add_f32_e32 v151, v151, v119
	v_mfma_f32_32x32x16_bf16 v[0:15], v[182:185], v[158:161], v[0:15]
	v_exp_f32_e32 v126, v126
	v_exp_f32_e32 v127, v127
	v_cvt_pk_bf16_f32 v158, v116, v117
	v_cvt_pk_bf16_f32 v159, v118, v119
	v_add_f32_e32 v140, v140, v120
	v_add_f32_e32 v151, v151, v121
	v_mfma_f32_32x32x16_bf16 v[64:79], v[178:181], v[162:165], v[64:79]
	v_exp_f32_e32 v128, v128
	v_exp_f32_e32 v129, v129
	v_cvt_pk_bf16_f32 v160, v120, v121
	v_cvt_pk_bf16_f32 v161, v122, v123
	v_add_f32_e32 v140, v140, v122
	v_add_f32_e32 v151, v151, v123
	v_mfma_f32_32x32x16_bf16 v[0:15], v[186:189], v[162:165], v[0:15]
	v_exp_f32_e32 v130, v130
	v_exp_f32_e32 v131, v131
	v_add_f32_e32 v140, v140, v124
	v_add_f32_e32 v151, v151, v125
	v_add_f32_e32 v140, v140, v126
	v_add_f32_e32 v151, v151, v127
	v_add_f32_e32 v140, v140, v128
	v_add_f32_e32 v151, v151, v129
	v_cvt_pk_bf16_f32 v162, v124, v125
	v_cvt_pk_bf16_f32 v163, v126, v127
	v_cvt_pk_bf16_f32 v164, v128, v129
	v_add_f32_e32 v140, v140, v130
	v_add_f32_e32 v151, v151, v131
	v_cvt_pk_bf16_f32 v165, v130, v131
	s_waitcnt lgkmcnt(0)
	v_mfma_f32_32x32x16_bf16 v[116:131], v[166:169], v[38:41], v[48:63]
	v_exp_f32_e32 v96, v96
	v_exp_f32_e32 v97, v97
	v_exp_f32_e32 v98, v98
	v_exp_f32_e32 v99, v99
	v_mfma_f32_32x32x16_bf16 v[116:131], v[170:173], v[34:37], v[116:131]
	v_exp_f32_e32 v100, v100
	v_exp_f32_e32 v101, v101
	v_exp_f32_e32 v102, v102
	v_exp_f32_e32 v103, v103
	ds_read_b128 v[166:169], v146
	ds_read_b128 v[170:173], v147
	v_mfma_f32_32x32x16_bf16 v[80:95], v[174:177], v[158:161], v[80:95]
	v_exp_f32_e32 v104, v104
	v_exp_f32_e32 v105, v105
	v_add_f32_e32 v141, v141, v96
	v_add_f32_e32 v150, v150, v97
	v_add_f32_e32 v141, v141, v98
	v_add_f32_e32 v150, v150, v99
	v_mfma_f32_32x32x16_bf16 v[16:31], v[182:185], v[158:161], v[16:31]
	v_exp_f32_e32 v106, v106
	v_exp_f32_e32 v107, v107
	v_cvt_pk_bf16_f32 v158, v96, v97
	v_cvt_pk_bf16_f32 v159, v98, v99
	v_add_f32_e32 v141, v141, v100
	v_add_f32_e32 v150, v150, v101
	v_mfma_f32_32x32x16_bf16 v[80:95], v[178:181], v[162:165], v[80:95]
	v_exp_f32_e32 v108, v108
	v_exp_f32_e32 v109, v109
	v_cvt_pk_bf16_f32 v160, v100, v101
	v_cvt_pk_bf16_f32 v161, v102, v103
	v_add_f32_e32 v141, v141, v102
	v_add_f32_e32 v150, v150, v103
	v_mfma_f32_32x32x16_bf16 v[16:31], v[186:189], v[162:165], v[16:31]
	ds_read_b128 v[174:177], v148 offset:40960
	ds_read_b128 v[178:181], v149 offset:40960
	ds_read_b128 v[182:185], v148 offset:45056
	ds_read_b128 v[186:189], v149 offset:45056
	v_exp_f32_e32 v110, v110
	v_exp_f32_e32 v111, v111
	v_add_f32_e32 v141, v141, v104
	v_add_f32_e32 v150, v150, v105
	v_add_f32_e32 v141, v141, v106
	v_add_f32_e32 v150, v150, v107
	v_add_f32_e32 v141, v141, v108
	v_add_f32_e32 v150, v150, v109
	v_cvt_pk_bf16_f32 v162, v104, v105
	v_cvt_pk_bf16_f32 v163, v106, v107
	v_cvt_pk_bf16_f32 v164, v108, v109
	v_add_f32_e32 v141, v141, v110
	v_add_f32_e32 v150, v150, v111
	v_cvt_pk_bf16_f32 v165, v110, v111
	s_waitcnt lgkmcnt(4)
	v_mfma_f32_32x32x16_bf16 v[96:111], v[166:169], v[112:115], v[48:63]
	v_exp_f32_e32 v116, v116
	v_exp_f32_e32 v117, v117
	v_exp_f32_e32 v118, v118
	v_exp_f32_e32 v119, v119
	v_mfma_f32_32x32x16_bf16 v[96:111], v[170:173], v[42:45], v[96:111]
	v_exp_f32_e32 v120, v120
	v_exp_f32_e32 v121, v121
	v_exp_f32_e32 v122, v122
	v_exp_f32_e32 v123, v123
	ds_read_b128 v[166:169], v148
	ds_read_b128 v[170:173], v149
	s_waitcnt lgkmcnt(2)
	v_mfma_f32_32x32x16_bf16 v[64:79], v[174:177], v[158:161], v[64:79]
	v_exp_f32_e32 v124, v124
	v_exp_f32_e32 v125, v125
	v_add_f32_e32 v140, v140, v116
	v_add_f32_e32 v151, v151, v117
	v_add_f32_e32 v140, v140, v118
	v_add_f32_e32 v151, v151, v119
	v_mfma_f32_32x32x16_bf16 v[0:15], v[182:185], v[158:161], v[0:15]
	v_exp_f32_e32 v126, v126
	v_exp_f32_e32 v127, v127
	v_cvt_pk_bf16_f32 v158, v116, v117
	v_cvt_pk_bf16_f32 v159, v118, v119
	v_add_f32_e32 v140, v140, v120
	v_add_f32_e32 v151, v151, v121
	v_mfma_f32_32x32x16_bf16 v[64:79], v[178:181], v[162:165], v[64:79]
	v_exp_f32_e32 v128, v128
	v_exp_f32_e32 v129, v129
	v_cvt_pk_bf16_f32 v160, v120, v121
	v_cvt_pk_bf16_f32 v161, v122, v123
	v_add_f32_e32 v140, v140, v122
	v_add_f32_e32 v151, v151, v123
	v_mfma_f32_32x32x16_bf16 v[0:15], v[186:189], v[162:165], v[0:15]
	v_exp_f32_e32 v130, v130
	v_exp_f32_e32 v131, v131
	v_add_f32_e32 v140, v140, v124
	v_add_f32_e32 v151, v151, v125
	v_add_f32_e32 v140, v140, v126
	v_add_f32_e32 v151, v151, v127
	v_add_f32_e32 v140, v140, v128
	v_add_f32_e32 v151, v151, v129
	v_cvt_pk_bf16_f32 v162, v124, v125
	v_cvt_pk_bf16_f32 v163, v126, v127
	v_cvt_pk_bf16_f32 v164, v128, v129
	v_add_f32_e32 v140, v140, v130
	v_add_f32_e32 v151, v151, v131
	v_cvt_pk_bf16_f32 v165, v130, v131
	s_waitcnt vmcnt(0) lgkmcnt(0)
	s_barrier
	s_cmp_le_u32 s4, s5
	s_cbranch_scc1 .Lc_tile_ph0
	s_mov_b32 s9, 0
